# nt hint on the MLA epilogue output stores
# baseline (speedup 1.0000x reference)
; DI unsigned pack2(float a, float b) { F2 v = {a, b}; B2 r = __builtin_convertvector(v, B2); return __builtin_bit_cast(unsigned, r); }
;     ...
;       float lt = st.l + __shfl_xor(st.l, 32); float il = 1.f / lt;
; #pragma unroll
;       for (int eb = 0; eb < 4; ++eb)
; #pragma unroll
;         for (int g = 0; g < 4; ++g) {
;           U2 v = mku2(pack2(st.ot[eb][4 * g] * il, st.ot[eb][4 * g + 1] * il), pack2(st.ot[eb][4 * g + 2] * il, st.ot[eb][4 * g + 3] * il));
;           *(U2*)(omla + qrow * 512 + hd * 128 + eb * 32 + 8 * g + 4 * h) = v;
;         }
.LBB0_658:
	ds_bpermute_b32 v0, v152, v66
	s_lshl_b32 s20, s19, 1
	v_lshlrev_b64 v[68:69], 10, v[146:147]
	s_waitcnt lgkmcnt(0)
	v_add_f32_e32 v0, v66, v0
	v_div_scale_f32 v70, s[18:19], v0, v0, 1.0
	v_rcp_f32_e32 v71, v70
	v_lshl_add_u64 v[66:67], s[8:9], 0, v[68:69]
	v_div_scale_f32 v68, vcc, 1.0, v0, 1.0
	v_fma_f32 v69, -v70, v71, 1.0
	v_fmac_f32_e32 v71, v69, v71
	v_mul_f32_e32 v69, v68, v71
	v_fma_f32 v72, -v70, v69, v68
	v_fmac_f32_e32 v69, v72, v71
	v_fma_f32 v68, -v70, v69, v68
	v_div_fmas_f32 v68, v68, v71, v69
	v_div_fixup_f32 v68, v68, v0, 1.0
	v_lshl_add_u64 v[66:67], v[66:67], 0, s[20:21]
	v_lshlrev_b32_e32 v0, 1, v186
	v_pk_mul_f32 v[50:51], v[50:51], v[68:69] op_sel_hi:[1,0]
	v_pk_mul_f32 v[52:53], v[52:53], v[68:69] op_sel_hi:[1,0]
	v_pk_mul_f32 v[34:35], v[34:35], v[68:69] op_sel_hi:[1,0]
	v_pk_mul_f32 v[36:37], v[36:37], v[68:69] op_sel_hi:[1,0]
	v_pk_mul_f32 v[18:19], v[18:19], v[68:69] op_sel_hi:[1,0]
	v_pk_mul_f32 v[20:21], v[20:21], v[68:69] op_sel_hi:[1,0]
	v_pk_mul_f32 v[2:3], v[2:3], v[68:69] op_sel_hi:[1,0]
	v_pk_mul_f32 v[4:5], v[4:5], v[68:69] op_sel_hi:[1,0]
	v_lshl_add_u64 v[66:67], v[66:67], 0, v[0:1]
	v_cvt_pk_bf16_f32 v50, v50, v51
	v_cvt_pk_bf16_f32 v51, v52, v53
	v_cvt_pk_bf16_f32 v34, v34, v35
	v_cvt_pk_bf16_f32 v35, v36, v37
	v_cvt_pk_bf16_f32 v18, v18, v19
	v_cvt_pk_bf16_f32 v19, v20, v21
	v_cvt_pk_bf16_f32 v2, v2, v3
	v_cvt_pk_bf16_f32 v3, v4, v5
	global_store_dwordx2 v[66:67], v[50:51], off nt
	v_pk_mul_f32 v[50:51], v[54:55], v[68:69] op_sel_hi:[1,0]
	v_pk_mul_f32 v[52:53], v[56:57], v[68:69] op_sel_hi:[1,0]
	global_store_dwordx2 v[66:67], v[34:35], off offset:64 nt
	v_pk_mul_f32 v[34:35], v[38:39], v[68:69] op_sel_hi:[1,0]
	v_pk_mul_f32 v[36:37], v[40:41], v[68:69] op_sel_hi:[1,0]
	global_store_dwordx2 v[66:67], v[18:19], off offset:128 nt
	v_pk_mul_f32 v[18:19], v[22:23], v[68:69] op_sel_hi:[1,0]
	v_pk_mul_f32 v[20:21], v[24:25], v[68:69] op_sel_hi:[1,0]
	global_store_dwordx2 v[66:67], v[2:3], off offset:192 nt
	v_pk_mul_f32 v[2:3], v[6:7], v[68:69] op_sel_hi:[1,0]
	v_pk_mul_f32 v[4:5], v[8:9], v[68:69] op_sel_hi:[1,0]
	v_cvt_pk_bf16_f32 v50, v50, v51
	v_cvt_pk_bf16_f32 v51, v52, v53
	v_cvt_pk_bf16_f32 v34, v34, v35
	v_cvt_pk_bf16_f32 v35, v36, v37
	v_cvt_pk_bf16_f32 v18, v18, v19
	v_cvt_pk_bf16_f32 v19, v20, v21
	v_cvt_pk_bf16_f32 v2, v2, v3
	v_cvt_pk_bf16_f32 v3, v4, v5
	global_store_dwordx2 v[66:67], v[50:51], off offset:16 nt
	v_pk_mul_f32 v[50:51], v[58:59], v[68:69] op_sel_hi:[1,0]
	v_pk_mul_f32 v[52:53], v[60:61], v[68:69] op_sel_hi:[1,0]
	global_store_dwordx2 v[66:67], v[34:35], off offset:80 nt
	v_pk_mul_f32 v[34:35], v[42:43], v[68:69] op_sel_hi:[1,0]
	v_pk_mul_f32 v[36:37], v[44:45], v[68:69] op_sel_hi:[1,0]
	global_store_dwordx2 v[66:67], v[18:19], off offset:144 nt
	v_pk_mul_f32 v[18:19], v[26:27], v[68:69] op_sel_hi:[1,0]
	v_pk_mul_f32 v[20:21], v[28:29], v[68:69] op_sel_hi:[1,0]
	global_store_dwordx2 v[66:67], v[2:3], off offset:208 nt
	v_pk_mul_f32 v[2:3], v[10:11], v[68:69] op_sel_hi:[1,0]
	v_pk_mul_f32 v[4:5], v[12:13], v[68:69] op_sel_hi:[1,0]
	v_cvt_pk_bf16_f32 v50, v50, v51
	v_cvt_pk_bf16_f32 v51, v52, v53
	v_cvt_pk_bf16_f32 v34, v34, v35
	v_cvt_pk_bf16_f32 v35, v36, v37
	v_cvt_pk_bf16_f32 v18, v18, v19
	v_cvt_pk_bf16_f32 v19, v20, v21
	v_cvt_pk_bf16_f32 v2, v2, v3
	v_cvt_pk_bf16_f32 v3, v4, v5
	global_store_dwordx2 v[66:67], v[50:51], off offset:32 nt
	v_pk_mul_f32 v[50:51], v[62:63], v[68:69] op_sel_hi:[1,0]
	v_pk_mul_f32 v[52:53], v[64:65], v[68:69] op_sel_hi:[1,0]
	global_store_dwordx2 v[66:67], v[34:35], off offset:96 nt
	v_pk_mul_f32 v[34:35], v[46:47], v[68:69] op_sel_hi:[1,0]
	v_pk_mul_f32 v[36:37], v[48:49], v[68:69] op_sel_hi:[1,0]
	global_store_dwordx2 v[66:67], v[18:19], off offset:160 nt
	v_pk_mul_f32 v[18:19], v[30:31], v[68:69] op_sel_hi:[1,0]
	v_pk_mul_f32 v[20:21], v[32:33], v[68:69] op_sel_hi:[1,0]
	global_store_dwordx2 v[66:67], v[2:3], off offset:224 nt
	v_pk_mul_f32 v[2:3], v[14:15], v[68:69] op_sel_hi:[1,0]
	v_pk_mul_f32 v[4:5], v[16:17], v[68:69] op_sel_hi:[1,0]
	v_cvt_pk_bf16_f32 v50, v50, v51
	v_cvt_pk_bf16_f32 v51, v52, v53
	v_cvt_pk_bf16_f32 v34, v34, v35
	v_cvt_pk_bf16_f32 v35, v36, v37
	v_cvt_pk_bf16_f32 v18, v18, v19
	v_cvt_pk_bf16_f32 v19, v20, v21
	v_cvt_pk_bf16_f32 v2, v2, v3
	v_cvt_pk_bf16_f32 v3, v4, v5
	global_store_dwordx2 v[66:67], v[50:51], off offset:48 nt
	global_store_dwordx2 v[66:67], v[34:35], off offset:112 nt
	global_store_dwordx2 v[66:67], v[18:19], off offset:176 nt
	global_store_dwordx2 v[66:67], v[2:3], off offset:240 nt
